# speedup vs baseline: 1.0204x; 1.0165x over previous
; DEV u32x2 pack4(f32x4 a) { u32x2 w; w.x = cvt_pk_bf16(a[0], a[1]); w.y = cvt_pk_bf16(a[2], a[3]); return w; }
;     DEV void operator()(AccRef acc, const pg8::Unit& u, int wr, int wc, int fr, int fq) const {
;     ...
;                     for (int n = 0; n < 2; ++n) { f32x4 v = acc[ai][bj][m][n] * rs + *(const f32x4*)(bias + col0 + bj * 128 + n * 16);
;                         if (n == 0 && rope) { f32x4 pv;
; #pragma unroll
;                             for (int e = 0; e < 4; ++e) pv[e] = __shfl_xor(v[e], 32);
;                             const float sg = (fq < 2) ? -1.f : 1.f;
;                             v = v * cs + sg * (pv * sn); }
;                         *(u32x2*)(rowp + bj * 128 + n * 16) = pack4(v); } }
.LBB0_148:
	v_cvt_pk_bf16_f32 v4, v4, v5
	v_cvt_pk_bf16_f32 v5, v6, v7
	global_store_dwordx2 v[26:27], v[4:5], off offset:256
	v_mov_b32_e32 v4, v228
	v_mov_b32_e32 v5, v229
	v_mov_b32_e32 v6, v230
	v_mov_b32_e32 v7, v231
	s_and_b64 vcc, exec, s[0:1]
	s_mov_b32 s16, s8
	s_mov_b32 s4, s10
	s_mov_b64 s[20:21], s[14:15]
	s_mov_b64 s[18:19], s[12:13]
	v_pk_fma_f32 v[2:3], v[2:3], v[12:13], v[6:7]
	v_pk_fma_f32 v[0:1], v[0:1], v[24:25], v[4:5]
	s_nop 0
	v_cvt_pk_bf16_f32 v0, v0, v1
	v_cvt_pk_bf16_f32 v1, v2, v3
	global_store_dwordx2 v[26:27], v[0:1], off offset:288
	s_cbranch_vccnz .LBB0_209

; DEV u32x2 pack4(f32x4 a) { u32x2 w; w.x = cvt_pk_bf16(a[0], a[1]); w.y = cvt_pk_bf16(a[2], a[3]); return w; }
;     DEV void operator()(AccRef acc, const pg8::Unit& u, int wr, int wc, int fr, int fq) const { store_bf16_tile<0, false>(acc, O, ld, u.pm * 256 + wr * 64 + fr, u.pn * 256 + wc * 32 + 4 * fq, ss); }
;     DEV void operator()(AccRef acc, const pg8::Unit& u, int wr, int wc, int fr, int fq) const {
;         const int row0 = u.pm * 256 + wr * 64 + fr, col0 = u.pn * 256 + wc * 32 + 4 * fq;
;         const bool rope = (u.pn < 9) && ((wc & 1) == 0);
; #pragma unroll
;         for (int ai = 0; ai < 2; ++ai)
; #pragma unroll
;             for (int m = 0; m < 4; ++m) { const int row = row0 + ai * 128 + m * 16; u16* rowp = O + (size_t)row * 2560 + col0; const float rs = rowscale(ss, row);
;                 f32x4 cs = (f32x4){1.f, 1.f, 1.f, 1.f}, sn = (f32x4){0.f, 0.f, 0.f, 0.f};
;                 if (rope) { cs = *(const f32x4*)(cosT + row * 8 + 4 * (fq & 1)); sn = *(const f32x4*)(sinT + row * 8 + 4 * (fq & 1)); }
; #pragma unroll
;                 for (int bj = 0; bj < 2; ++bj)
; #pragma unroll
;                     for (int n = 0; n < 2; ++n) { f32x4 v = acc[ai][bj][m][n] * rs + *(const f32x4*)(bias + col0 + bj * 128 + n * 16);
;                         if (n == 0 && rope) { f32x4 pv;
; #pragma unroll
;                             for (int e = 0; e < 4; ++e) pv[e] = __shfl_xor(v[e], 32);
;                             const float sg = (fq < 2) ? -1.f : 1.f;
;                             v = v * cs + sg * (pv * sn); }
;                         *(u32x2*)(rowp + bj * 128 + n * 16) = pack4(v); } }
.LBB0_156:
	s_waitcnt vmcnt(0)
	v_mov_b32_e32 v180, v141
	v_mov_b32_e32 v181, v142
	v_mov_b32_e32 v141, v143
	v_pk_add_f32 v[140:141], v[180:181], v[140:141]
	v_mov_b32_e32 v142, v138
	v_mov_b32_e32 v143, v136
	v_mov_b32_e32 v136, v139
	v_pk_add_f32 v[136:137], v[142:143], v[136:137]
	v_add_f32_e32 v138, v140, v141
	v_add_f32_e32 v137, v138, v137
	v_add_f32_e32 v136, v136, v137
	v_fmamk_f32 v136, v136, 0x3a000000, v199
	s_mov_b32 s9, 0x800000
	v_cmp_gt_f32_e32 vcc, s9, v136
	v_mul_f32_e32 v137, 0x4b800000, v136
	v_lshl_or_b32 v158, s16, 8, v177
	v_cndmask_b32_e32 v136, v136, v137, vcc
	v_rsq_f32_e32 v136, v136
	v_ashrrev_i32_e32 v159, 31, v158
	v_mul_f32_e32 v137, 0x45800000, v136
	v_cndmask_b32_e32 v138, v136, v137, vcc
	v_lshl_add_u64 v[136:137], v[158:159], 2, s[48:49]
	global_load_dwordx4 v[216:219], v[136:137], off
	global_load_dwordx4 v[220:223], v[136:137], off offset:64
	global_load_dwordx4 v[224:227], v[136:137], off offset:512
	global_load_dwordx4 v[228:231], v[136:137], off offset:576
	s_and_b64 vcc, exec, s[4:5]
	s_waitcnt vmcnt(0)
	v_mov_b32_e32 v140, v216
	v_mov_b32_e32 v141, v217
	v_mov_b32_e32 v142, v218
	v_mov_b32_e32 v143, v219
	v_pk_fma_f32 v[126:127], v[126:127], v[138:139], v[142:143] op_sel_hi:[1,0,1]
	v_pk_fma_f32 v[124:125], v[124:125], v[138:139], v[140:141] op_sel_hi:[1,0,1]
	s_cbranch_vccnz .LBB0_158
	v_cmp_lt_i32_e32 vcc, v207, v206
	s_nop 1
	v_cndmask_b32_e32 v139, v204, v207, vcc
	v_lshlrev_b32_e32 v139, 2, v139
	ds_bpermute_b32 v140, v139, v124
	ds_bpermute_b32 v142, v139, v126
	ds_bpermute_b32 v143, v139, v127
	ds_bpermute_b32 v141, v139, v125
	s_waitcnt lgkmcnt(0)
	v_pk_mul_f32 v[142:143], v[134:135], v[142:143]
	v_pk_mul_f32 v[140:141], v[132:133], v[140:141]
	v_pk_mul_f32 v[142:143], v[148:149], v[142:143]
	v_pk_mul_f32 v[140:141], v[146:147], v[140:141]
	v_pk_fma_f32 v[126:127], v[130:131], v[126:127], v[142:143]
	v_pk_fma_f32 v[124:125], v[128:129], v[124:125], v[140:141]
.LBB0_158:
	v_readlane_b32 s18, v250, 11
	v_readlane_b32 s19, v250, 12
	v_cvt_pk_bf16_f32 v124, v124, v125
	v_cvt_pk_bf16_f32 v125, v126, v127
	v_mov_b64_e32 v[140:141], s[18:19]
	v_mad_i64_i32 v[140:141], s[18:19], v174, s96, v[140:141]
	v_lshl_add_u64 v[140:141], v[158:159], 1, v[140:141]
	global_store_dwordx2 v[140:141], v[124:125], off
	v_mov_b32_e32 v180, v220
	v_mov_b32_e32 v181, v221
	v_mov_b32_e32 v182, v222
	v_mov_b32_e32 v183, v223
	v_mov_b32_e32 v139, v138
	v_mov_b32_e32 v124, v138
	v_mov_b32_e32 v125, v138
	s_and_b64 vcc, exec, s[4:5]
	v_pk_fma_f32 v[122:123], v[122:123], v[124:125], v[182:183]
	v_pk_fma_f32 v[120:121], v[120:121], v[138:139], v[180:181]
	s_nop 0
	v_cvt_pk_bf16_f32 v120, v120, v121
	v_cvt_pk_bf16_f32 v121, v122, v123
	global_store_dwordx2 v[140:141], v[120:121], off offset:32
	v_mov_b32_e32 v120, v224
	v_mov_b32_e32 v121, v225
	v_mov_b32_e32 v122, v226
	v_mov_b32_e32 v123, v227
	v_pk_fma_f32 v[118:119], v[118:119], v[124:125], v[122:123]
	v_pk_fma_f32 v[116:117], v[116:117], v[138:139], v[120:121]
	s_cbranch_vccnz .LBB0_160
	v_cmp_lt_i32_e32 vcc, v207, v206
	s_nop 1
	v_cndmask_b32_e32 v120, v204, v207, vcc
	v_lshlrev_b32_e32 v121, 2, v120
	ds_bpermute_b32 v120, v121, v116
	ds_bpermute_b32 v122, v121, v118
	ds_bpermute_b32 v123, v121, v119
	ds_bpermute_b32 v121, v121, v117
	s_waitcnt lgkmcnt(0)
	v_pk_mul_f32 v[122:123], v[134:135], v[122:123]
	v_pk_mul_f32 v[120:121], v[132:133], v[120:121]
	v_pk_mul_f32 v[122:123], v[148:149], v[122:123]
	v_pk_mul_f32 v[120:121], v[146:147], v[120:121]
	v_pk_fma_f32 v[118:119], v[130:131], v[118:119], v[122:123]
	v_pk_fma_f32 v[116:117], v[128:129], v[116:117], v[120:121]
.LBB0_160:
	s_nop 0
	v_cvt_pk_bf16_f32 v116, v116, v117
	v_cvt_pk_bf16_f32 v117, v118, v119
	global_store_dwordx2 v[140:141], v[116:117], off offset:256
	v_mov_b32_e32 v116, v228
	v_mov_b32_e32 v117, v229
	v_mov_b32_e32 v118, v230
	v_mov_b32_e32 v119, v231
	v_or_b32_e32 v128, 16, v174
	v_ashrrev_i32_e32 v129, 31, v128
	s_and_b64 vcc, exec, s[4:5]
	v_pk_fma_f32 v[114:115], v[114:115], v[124:125], v[118:119]
	v_pk_fma_f32 v[112:113], v[112:113], v[138:139], v[116:117]
	s_nop 0
	v_cvt_pk_bf16_f32 v112, v112, v113
	v_cvt_pk_bf16_f32 v113, v114, v115
	global_store_dwordx2 v[140:141], v[112:113], off offset:288
	v_lshlrev_b64 v[112:113], 5, v[128:129]
	v_lshl_add_u64 v[112:113], s[20:21], 0, v[112:113]
	global_load_dwordx4 v[120:123], v[112:113], off offset:16
	global_load_dwordx4 v[124:127], v[112:113], off
	s_cbranch_vccnz .LBB0_162
	v_lshlrev_b32_e32 v112, 3, v128
	v_ashrrev_i32_e32 v113, 31, v112
	v_lshlrev_b64 v[112:113], 2, v[112:113]
	v_lshl_add_u64 v[114:115], v[152:153], 0, v[112:113]
	v_lshl_add_u64 v[116:117], v[150:151], 0, v[112:113]
	global_load_dwordx4 v[112:115], v[114:115], off
	s_nop 0
	global_load_dwordx4 v[116:119], v[116:117], off
	s_branch .LBB0_163

; DEV u32x2 pack4(f32x4 a) { u32x2 w; w.x = cvt_pk_bf16(a[0], a[1]); w.y = cvt_pk_bf16(a[2], a[3]); return w; }
;     DEV void operator()(AccRef acc, const pg8::Unit& u, int wr, int wc, int fr, int fq) const {
;     ...
;             for (int m = 0; m < 4; ++m) { const int row = row0 + ai * 128 + m * 16; u16* rowp = O + (size_t)row * 2560 + col0; const float rs = rowscale(ss, row);
;                 f32x4 cs = (f32x4){1.f, 1.f, 1.f, 1.f}, sn = (f32x4){0.f, 0.f, 0.f, 0.f};
;                 if (rope) { cs = *(const f32x4*)(cosT + row * 8 + 4 * (fq & 1)); sn = *(const f32x4*)(sinT + row * 8 + 4 * (fq & 1)); }
; #pragma unroll
;                 for (int bj = 0; bj < 2; ++bj)
; #pragma unroll
;                     for (int n = 0; n < 2; ++n) { f32x4 v = acc[ai][bj][m][n] * rs + *(const f32x4*)(bias + col0 + bj * 128 + n * 16);
;                         if (n == 0 && rope) { f32x4 pv;
; #pragma unroll
;                             for (int e = 0; e < 4; ++e) pv[e] = __shfl_xor(v[e], 32);
;                             const float sg = (fq < 2) ? -1.f : 1.f;
;                             v = v * cs + sg * (pv * sn); }
;                         *(u32x2*)(rowp + bj * 128 + n * 16) = pack4(v); } }
.LBB0_163:
	s_waitcnt vmcnt(0)
	v_mov_b32_e32 v130, v125
	v_mov_b32_e32 v131, v126
	v_mov_b32_e32 v125, v127
	v_pk_add_f32 v[124:125], v[130:131], v[124:125]
	v_mov_b32_e32 v126, v122
	v_mov_b32_e32 v127, v120
	v_mov_b32_e32 v120, v123
	v_pk_add_f32 v[120:121], v[126:127], v[120:121]
	v_add_f32_e32 v122, v124, v125
	v_add_f32_e32 v121, v122, v121
	v_mov_b32_e32 v122, v216
	v_mov_b32_e32 v123, v217
	v_mov_b32_e32 v124, v218
	v_mov_b32_e32 v125, v219
	v_add_f32_e32 v120, v120, v121
	v_fmamk_f32 v120, v120, 0x3a000000, v199
	v_cmp_gt_f32_e32 vcc, s9, v120
	v_mul_f32_e32 v121, 0x4b800000, v120
	s_nop 0
	v_cndmask_b32_e32 v120, v120, v121, vcc
	v_rsq_f32_e32 v120, v120
	s_nop 0
	v_mul_f32_e32 v121, 0x45800000, v120
	v_cndmask_b32_e32 v120, v120, v121, vcc
	s_and_b64 vcc, exec, s[4:5]
	v_pk_fma_f32 v[110:111], v[110:111], v[120:121], v[124:125] op_sel_hi:[1,0,1]
	v_pk_fma_f32 v[108:109], v[108:109], v[120:121], v[122:123] op_sel_hi:[1,0,1]
	s_cbranch_vccnz .LBB0_165
	v_cmp_lt_i32_e32 vcc, v207, v206
	s_nop 1
	v_cndmask_b32_e32 v121, v204, v207, vcc
	v_lshlrev_b32_e32 v121, 2, v121
	ds_bpermute_b32 v122, v121, v108
	ds_bpermute_b32 v124, v121, v110
	ds_bpermute_b32 v125, v121, v111
	ds_bpermute_b32 v123, v121, v109
	s_waitcnt lgkmcnt(0)
	v_pk_mul_f32 v[124:125], v[118:119], v[124:125]
	v_pk_mul_f32 v[122:123], v[116:117], v[122:123]
	v_pk_mul_f32 v[124:125], v[148:149], v[124:125]
	v_pk_mul_f32 v[122:123], v[146:147], v[122:123]
	v_pk_fma_f32 v[110:111], v[114:115], v[110:111], v[124:125]
	v_pk_fma_f32 v[108:109], v[112:113], v[108:109], v[122:123]
.LBB0_165:
	v_readlane_b32 s18, v250, 11
	v_readlane_b32 s19, v250, 12
	v_cvt_pk_bf16_f32 v108, v108, v109
	v_cvt_pk_bf16_f32 v109, v110, v111
	v_mov_b64_e32 v[122:123], s[18:19]
	v_mad_i64_i32 v[122:123], s[18:19], v128, s96, v[122:123]
	v_lshl_add_u64 v[122:123], v[158:159], 1, v[122:123]
	global_store_dwordx2 v[122:123], v[108:109], off
	v_mov_b32_e32 v124, v220
	v_mov_b32_e32 v125, v221
	v_mov_b32_e32 v126, v222
	v_mov_b32_e32 v127, v223
	v_mov_b32_e32 v121, v120
	v_mov_b32_e32 v108, v120
	v_mov_b32_e32 v109, v120
	s_and_b64 vcc, exec, s[4:5]
	v_pk_fma_f32 v[106:107], v[106:107], v[108:109], v[126:127]
	v_pk_fma_f32 v[104:105], v[104:105], v[120:121], v[124:125]
	s_nop 0
	v_cvt_pk_bf16_f32 v104, v104, v105
	v_cvt_pk_bf16_f32 v105, v106, v107
	global_store_dwordx2 v[122:123], v[104:105], off offset:32
	v_mov_b32_e32 v104, v224
	v_mov_b32_e32 v105, v225
	v_mov_b32_e32 v106, v226
	v_mov_b32_e32 v107, v227
	v_pk_fma_f32 v[102:103], v[102:103], v[108:109], v[106:107]
	v_pk_fma_f32 v[100:101], v[100:101], v[120:121], v[104:105]
	s_cbranch_vccnz .LBB0_167
	v_cmp_lt_i32_e32 vcc, v207, v206
	s_nop 1
	v_cndmask_b32_e32 v104, v204, v207, vcc
	v_lshlrev_b32_e32 v105, 2, v104
	ds_bpermute_b32 v104, v105, v100
	ds_bpermute_b32 v106, v105, v102
	ds_bpermute_b32 v107, v105, v103
	ds_bpermute_b32 v105, v105, v101
	s_waitcnt lgkmcnt(0)
	v_pk_mul_f32 v[106:107], v[118:119], v[106:107]
	v_pk_mul_f32 v[104:105], v[116:117], v[104:105]
	v_pk_mul_f32 v[106:107], v[148:149], v[106:107]
	v_pk_mul_f32 v[104:105], v[146:147], v[104:105]
	v_pk_fma_f32 v[102:103], v[114:115], v[102:103], v[106:107]
	v_pk_fma_f32 v[100:101], v[112:113], v[100:101], v[104:105]
.LBB0_167:
	s_nop 0
	v_cvt_pk_bf16_f32 v100, v100, v101
	v_cvt_pk_bf16_f32 v101, v102, v103
	global_store_dwordx2 v[122:123], v[100:101], off offset:256
	v_mov_b32_e32 v100, v228
	v_mov_b32_e32 v101, v229
	v_mov_b32_e32 v102, v230
	v_mov_b32_e32 v103, v231
	v_or_b32_e32 v112, 32, v174
	v_ashrrev_i32_e32 v113, 31, v112
	s_and_b64 vcc, exec, s[4:5]
	v_pk_fma_f32 v[98:99], v[98:99], v[108:109], v[102:103]
	v_pk_fma_f32 v[96:97], v[96:97], v[120:121], v[100:101]
	s_nop 0
	v_cvt_pk_bf16_f32 v96, v96, v97
	v_cvt_pk_bf16_f32 v97, v98, v99
	global_store_dwordx2 v[122:123], v[96:97], off offset:288
	v_lshlrev_b64 v[96:97], 5, v[112:113]
	v_lshl_add_u64 v[96:97], s[20:21], 0, v[96:97]
	global_load_dwordx4 v[104:107], v[96:97], off offset:16
	global_load_dwordx4 v[108:111], v[96:97], off
	s_cbranch_vccnz .LBB0_169
	v_lshlrev_b32_e32 v96, 3, v112
	v_ashrrev_i32_e32 v97, 31, v96
	v_lshlrev_b64 v[96:97], 2, v[96:97]
	v_lshl_add_u64 v[98:99], v[152:153], 0, v[96:97]
	v_lshl_add_u64 v[100:101], v[150:151], 0, v[96:97]
	global_load_dwordx4 v[96:99], v[98:99], off
	s_nop 0
	global_load_dwordx4 v[100:103], v[100:101], off
	s_branch .LBB0_170

; DEV u32x2 pack4(f32x4 a) { u32x2 w; w.x = cvt_pk_bf16(a[0], a[1]); w.y = cvt_pk_bf16(a[2], a[3]); return w; }
;     DEV void operator()(AccRef acc, const pg8::Unit& u, int wr, int wc, int fr, int fq) const {
;     ...
;             for (int m = 0; m < 4; ++m) { const int row = row0 + ai * 128 + m * 16; u16* rowp = O + (size_t)row * 2560 + col0; const float rs = rowscale(ss, row);
;                 f32x4 cs = (f32x4){1.f, 1.f, 1.f, 1.f}, sn = (f32x4){0.f, 0.f, 0.f, 0.f};
;                 if (rope) { cs = *(const f32x4*)(cosT + row * 8 + 4 * (fq & 1)); sn = *(const f32x4*)(sinT + row * 8 + 4 * (fq & 1)); }
; #pragma unroll
;                 for (int bj = 0; bj < 2; ++bj)
; #pragma unroll
;                     for (int n = 0; n < 2; ++n) { f32x4 v = acc[ai][bj][m][n] * rs + *(const f32x4*)(bias + col0 + bj * 128 + n * 16);
;                         if (n == 0 && rope) { f32x4 pv;
; #pragma unroll
;                             for (int e = 0; e < 4; ++e) pv[e] = __shfl_xor(v[e], 32);
;                             const float sg = (fq < 2) ? -1.f : 1.f;
;                             v = v * cs + sg * (pv * sn); }
;                         *(u32x2*)(rowp + bj * 128 + n * 16) = pack4(v); } }
.LBB0_170:
	s_waitcnt vmcnt(0)
	v_mov_b32_e32 v114, v109
	v_mov_b32_e32 v115, v110
	v_mov_b32_e32 v109, v111
	v_pk_add_f32 v[108:109], v[114:115], v[108:109]
	v_mov_b32_e32 v110, v106
	v_mov_b32_e32 v111, v104
	v_mov_b32_e32 v104, v107
	v_pk_add_f32 v[104:105], v[110:111], v[104:105]
	v_add_f32_e32 v106, v108, v109
	v_add_f32_e32 v105, v106, v105
	v_mov_b32_e32 v106, v216
	v_mov_b32_e32 v107, v217
	v_mov_b32_e32 v108, v218
	v_mov_b32_e32 v109, v219
	v_add_f32_e32 v104, v104, v105
	v_fmamk_f32 v104, v104, 0x3a000000, v199
	v_cmp_gt_f32_e32 vcc, s9, v104
	v_mul_f32_e32 v105, 0x4b800000, v104
	s_nop 0
	v_cndmask_b32_e32 v104, v104, v105, vcc
	v_rsq_f32_e32 v104, v104
	s_nop 0
	v_mul_f32_e32 v105, 0x45800000, v104
	v_cndmask_b32_e32 v104, v104, v105, vcc
	s_and_b64 vcc, exec, s[4:5]
	v_pk_fma_f32 v[94:95], v[94:95], v[104:105], v[108:109] op_sel_hi:[1,0,1]
	v_pk_fma_f32 v[92:93], v[92:93], v[104:105], v[106:107] op_sel_hi:[1,0,1]
	s_cbranch_vccnz .LBB0_172
	v_cmp_lt_i32_e32 vcc, v207, v206
	s_nop 1
	v_cndmask_b32_e32 v105, v204, v207, vcc
	v_lshlrev_b32_e32 v105, 2, v105
	ds_bpermute_b32 v106, v105, v92
	ds_bpermute_b32 v108, v105, v94
	ds_bpermute_b32 v109, v105, v95
	ds_bpermute_b32 v107, v105, v93
	s_waitcnt lgkmcnt(0)
	v_pk_mul_f32 v[108:109], v[102:103], v[108:109]
	v_pk_mul_f32 v[106:107], v[100:101], v[106:107]
	v_pk_mul_f32 v[108:109], v[148:149], v[108:109]
	v_pk_mul_f32 v[106:107], v[146:147], v[106:107]
	v_pk_fma_f32 v[94:95], v[98:99], v[94:95], v[108:109]
	v_pk_fma_f32 v[92:93], v[96:97], v[92:93], v[106:107]
.LBB0_172:
	v_readlane_b32 s18, v250, 11
	v_readlane_b32 s19, v250, 12
	v_cvt_pk_bf16_f32 v92, v92, v93
	v_cvt_pk_bf16_f32 v93, v94, v95
	v_mov_b64_e32 v[106:107], s[18:19]
	v_mad_i64_i32 v[106:107], s[18:19], v112, s96, v[106:107]
	v_lshl_add_u64 v[106:107], v[158:159], 1, v[106:107]
	global_store_dwordx2 v[106:107], v[92:93], off
	v_mov_b32_e32 v108, v220
	v_mov_b32_e32 v109, v221
	v_mov_b32_e32 v110, v222
	v_mov_b32_e32 v111, v223
	v_mov_b32_e32 v105, v104
	v_mov_b32_e32 v92, v104
	v_mov_b32_e32 v93, v104
	s_and_b64 vcc, exec, s[4:5]
	v_pk_fma_f32 v[90:91], v[90:91], v[92:93], v[110:111]
	v_pk_fma_f32 v[88:89], v[88:89], v[104:105], v[108:109]
	s_nop 0
	v_cvt_pk_bf16_f32 v88, v88, v89
	v_cvt_pk_bf16_f32 v89, v90, v91
	global_store_dwordx2 v[106:107], v[88:89], off offset:32
	v_mov_b32_e32 v88, v224
	v_mov_b32_e32 v89, v225
	v_mov_b32_e32 v90, v226
	v_mov_b32_e32 v91, v227
	v_pk_fma_f32 v[86:87], v[86:87], v[92:93], v[90:91]
	v_pk_fma_f32 v[84:85], v[84:85], v[104:105], v[88:89]
	s_cbranch_vccnz .LBB0_174
	v_cmp_lt_i32_e32 vcc, v207, v206
	s_nop 1
	v_cndmask_b32_e32 v88, v204, v207, vcc
	v_lshlrev_b32_e32 v89, 2, v88
	ds_bpermute_b32 v88, v89, v84
	ds_bpermute_b32 v90, v89, v86
	ds_bpermute_b32 v91, v89, v87
	ds_bpermute_b32 v89, v89, v85
	s_waitcnt lgkmcnt(0)
	v_pk_mul_f32 v[90:91], v[102:103], v[90:91]
	v_pk_mul_f32 v[88:89], v[100:101], v[88:89]
	v_pk_mul_f32 v[90:91], v[148:149], v[90:91]
	v_pk_mul_f32 v[88:89], v[146:147], v[88:89]
	v_pk_fma_f32 v[86:87], v[98:99], v[86:87], v[90:91]
	v_pk_fma_f32 v[84:85], v[96:97], v[84:85], v[88:89]
.LBB0_174:
	s_nop 0
	v_cvt_pk_bf16_f32 v84, v84, v85
	v_cvt_pk_bf16_f32 v85, v86, v87
	global_store_dwordx2 v[106:107], v[84:85], off offset:256
	v_mov_b32_e32 v84, v228
	v_mov_b32_e32 v85, v229
	v_mov_b32_e32 v86, v230
	v_mov_b32_e32 v87, v231
	v_or_b32_e32 v96, 48, v174
	v_ashrrev_i32_e32 v97, 31, v96
	s_and_b64 vcc, exec, s[4:5]
	v_pk_fma_f32 v[82:83], v[82:83], v[92:93], v[86:87]
	v_pk_fma_f32 v[80:81], v[80:81], v[104:105], v[84:85]
	s_nop 0
	v_cvt_pk_bf16_f32 v80, v80, v81
	v_cvt_pk_bf16_f32 v81, v82, v83
	global_store_dwordx2 v[106:107], v[80:81], off offset:288
	v_lshlrev_b64 v[80:81], 5, v[96:97]
	v_lshl_add_u64 v[80:81], s[20:21], 0, v[80:81]
	global_load_dwordx4 v[88:91], v[80:81], off offset:16
	global_load_dwordx4 v[92:95], v[80:81], off
	s_cbranch_vccnz .LBB0_176
	v_lshlrev_b32_e32 v80, 3, v96
	v_ashrrev_i32_e32 v81, 31, v80
	v_lshlrev_b64 v[80:81], 2, v[80:81]
	v_lshl_add_u64 v[82:83], v[152:153], 0, v[80:81]
	v_lshl_add_u64 v[84:85], v[150:151], 0, v[80:81]
	global_load_dwordx4 v[80:83], v[82:83], off
	s_nop 0
	global_load_dwordx4 v[84:87], v[84:85], off
	s_branch .LBB0_177

; DEV u32x2 pack4(f32x4 a) { u32x2 w; w.x = cvt_pk_bf16(a[0], a[1]); w.y = cvt_pk_bf16(a[2], a[3]); return w; }
;     DEV void operator()(AccRef acc, const pg8::Unit& u, int wr, int wc, int fr, int fq) const {
;     ...
;             for (int m = 0; m < 4; ++m) { const int row = row0 + ai * 128 + m * 16; u16* rowp = O + (size_t)row * 2560 + col0; const float rs = rowscale(ss, row);
;                 f32x4 cs = (f32x4){1.f, 1.f, 1.f, 1.f}, sn = (f32x4){0.f, 0.f, 0.f, 0.f};
;                 if (rope) { cs = *(const f32x4*)(cosT + row * 8 + 4 * (fq & 1)); sn = *(const f32x4*)(sinT + row * 8 + 4 * (fq & 1)); }
; #pragma unroll
;                 for (int bj = 0; bj < 2; ++bj)
; #pragma unroll
;                     for (int n = 0; n < 2; ++n) { f32x4 v = acc[ai][bj][m][n] * rs + *(const f32x4*)(bias + col0 + bj * 128 + n * 16);
;                         if (n == 0 && rope) { f32x4 pv;
; #pragma unroll
;                             for (int e = 0; e < 4; ++e) pv[e] = __shfl_xor(v[e], 32);
;                             const float sg = (fq < 2) ? -1.f : 1.f;
;                             v = v * cs + sg * (pv * sn); }
;                         *(u32x2*)(rowp + bj * 128 + n * 16) = pack4(v); } }
.LBB0_177:
	s_waitcnt vmcnt(0)
	v_mov_b32_e32 v98, v93
	v_mov_b32_e32 v99, v94
	v_mov_b32_e32 v93, v95
	v_pk_add_f32 v[92:93], v[98:99], v[92:93]
	v_mov_b32_e32 v94, v90
	v_mov_b32_e32 v95, v88
	v_mov_b32_e32 v88, v91
	v_pk_add_f32 v[88:89], v[94:95], v[88:89]
	v_add_f32_e32 v90, v92, v93
	v_add_f32_e32 v89, v90, v89
	v_mov_b32_e32 v90, v216
	v_mov_b32_e32 v91, v217
	v_mov_b32_e32 v92, v218
	v_mov_b32_e32 v93, v219
	v_add_f32_e32 v88, v88, v89
	v_fmamk_f32 v88, v88, 0x3a000000, v199
	v_cmp_gt_f32_e32 vcc, s9, v88
	v_mul_f32_e32 v89, 0x4b800000, v88
	s_nop 0
	v_cndmask_b32_e32 v88, v88, v89, vcc
	v_rsq_f32_e32 v88, v88
	s_nop 0
	v_mul_f32_e32 v89, 0x45800000, v88
	v_cndmask_b32_e32 v88, v88, v89, vcc
	s_and_b64 vcc, exec, s[4:5]
	v_pk_fma_f32 v[78:79], v[78:79], v[88:89], v[92:93] op_sel_hi:[1,0,1]
	v_pk_fma_f32 v[76:77], v[76:77], v[88:89], v[90:91] op_sel_hi:[1,0,1]
	s_cbranch_vccnz .LBB0_179
	v_cmp_lt_i32_e32 vcc, v207, v206
	s_nop 1
	v_cndmask_b32_e32 v89, v204, v207, vcc
	v_lshlrev_b32_e32 v89, 2, v89
	ds_bpermute_b32 v90, v89, v76
	ds_bpermute_b32 v92, v89, v78
	ds_bpermute_b32 v93, v89, v79
	ds_bpermute_b32 v91, v89, v77
	s_waitcnt lgkmcnt(0)
	v_pk_mul_f32 v[92:93], v[86:87], v[92:93]
	v_pk_mul_f32 v[90:91], v[84:85], v[90:91]
	v_pk_mul_f32 v[92:93], v[148:149], v[92:93]
	v_pk_mul_f32 v[90:91], v[146:147], v[90:91]
	v_pk_fma_f32 v[78:79], v[82:83], v[78:79], v[92:93]
	v_pk_fma_f32 v[76:77], v[80:81], v[76:77], v[90:91]
.LBB0_179:
	v_readlane_b32 s18, v250, 11
	v_readlane_b32 s19, v250, 12
	v_cvt_pk_bf16_f32 v76, v76, v77
	v_cvt_pk_bf16_f32 v77, v78, v79
	v_mov_b64_e32 v[90:91], s[18:19]
	v_mad_i64_i32 v[90:91], s[18:19], v96, s96, v[90:91]
	v_lshl_add_u64 v[90:91], v[158:159], 1, v[90:91]
	global_store_dwordx2 v[90:91], v[76:77], off
	v_mov_b32_e32 v92, v220
	v_mov_b32_e32 v93, v221
	v_mov_b32_e32 v94, v222
	v_mov_b32_e32 v95, v223
	v_mov_b32_e32 v89, v88
	v_mov_b32_e32 v76, v88
	v_mov_b32_e32 v77, v88
	s_and_b64 vcc, exec, s[4:5]
	v_pk_fma_f32 v[74:75], v[74:75], v[76:77], v[94:95]
	v_pk_fma_f32 v[72:73], v[72:73], v[88:89], v[92:93]
	s_nop 0
	v_cvt_pk_bf16_f32 v72, v72, v73
	v_cvt_pk_bf16_f32 v73, v74, v75
	global_store_dwordx2 v[90:91], v[72:73], off offset:32
	v_mov_b32_e32 v72, v224
	v_mov_b32_e32 v73, v225
	v_mov_b32_e32 v74, v226
	v_mov_b32_e32 v75, v227
	v_pk_fma_f32 v[70:71], v[70:71], v[76:77], v[74:75]
	v_pk_fma_f32 v[68:69], v[68:69], v[88:89], v[72:73]
	s_cbranch_vccnz .LBB0_181
	v_cmp_lt_i32_e32 vcc, v207, v206
	s_nop 1
	v_cndmask_b32_e32 v72, v204, v207, vcc
	v_lshlrev_b32_e32 v73, 2, v72
	ds_bpermute_b32 v72, v73, v68
	ds_bpermute_b32 v74, v73, v70
	ds_bpermute_b32 v75, v73, v71
	ds_bpermute_b32 v73, v73, v69
	s_waitcnt lgkmcnt(0)
	v_pk_mul_f32 v[74:75], v[86:87], v[74:75]
	v_pk_mul_f32 v[72:73], v[84:85], v[72:73]
	v_pk_mul_f32 v[74:75], v[148:149], v[74:75]
	v_pk_mul_f32 v[72:73], v[146:147], v[72:73]
	v_pk_fma_f32 v[70:71], v[82:83], v[70:71], v[74:75]
	v_pk_fma_f32 v[68:69], v[80:81], v[68:69], v[72:73]
.LBB0_181:
	s_nop 0
	v_cvt_pk_bf16_f32 v68, v68, v69
	v_cvt_pk_bf16_f32 v69, v70, v71
	global_store_dwordx2 v[90:91], v[68:69], off offset:256
	v_mov_b32_e32 v68, v228
	v_mov_b32_e32 v69, v229
	v_mov_b32_e32 v70, v230
	v_mov_b32_e32 v71, v231
	v_add_u32_e32 v80, 0x80, v174
	v_ashrrev_i32_e32 v81, 31, v80
	s_and_b64 vcc, exec, s[4:5]
	v_pk_fma_f32 v[66:67], v[66:67], v[76:77], v[70:71]
	v_pk_fma_f32 v[64:65], v[64:65], v[88:89], v[68:69]
	s_nop 0
	v_cvt_pk_bf16_f32 v64, v64, v65
	v_cvt_pk_bf16_f32 v65, v66, v67
	global_store_dwordx2 v[90:91], v[64:65], off offset:288
	v_lshlrev_b64 v[64:65], 5, v[80:81]
	v_lshl_add_u64 v[64:65], s[20:21], 0, v[64:65]
	global_load_dwordx4 v[72:75], v[64:65], off offset:16
	global_load_dwordx4 v[76:79], v[64:65], off
	s_cbranch_vccnz .LBB0_183
	v_lshlrev_b32_e32 v64, 3, v80
	v_ashrrev_i32_e32 v65, 31, v64
	v_lshlrev_b64 v[64:65], 2, v[64:65]
	v_lshl_add_u64 v[66:67], v[152:153], 0, v[64:65]
	v_lshl_add_u64 v[68:69], v[150:151], 0, v[64:65]
	global_load_dwordx4 v[64:67], v[66:67], off
	s_nop 0
	global_load_dwordx4 v[68:71], v[68:69], off
	s_branch .LBB0_184

; DEV u32x2 pack4(f32x4 a) { u32x2 w; w.x = cvt_pk_bf16(a[0], a[1]); w.y = cvt_pk_bf16(a[2], a[3]); return w; }
;     DEV void operator()(AccRef acc, const pg8::Unit& u, int wr, int wc, int fr, int fq) const {
;     ...
;             for (int m = 0; m < 4; ++m) { const int row = row0 + ai * 128 + m * 16; u16* rowp = O + (size_t)row * 2560 + col0; const float rs = rowscale(ss, row);
;                 f32x4 cs = (f32x4){1.f, 1.f, 1.f, 1.f}, sn = (f32x4){0.f, 0.f, 0.f, 0.f};
;                 if (rope) { cs = *(const f32x4*)(cosT + row * 8 + 4 * (fq & 1)); sn = *(const f32x4*)(sinT + row * 8 + 4 * (fq & 1)); }
; #pragma unroll
;                 for (int bj = 0; bj < 2; ++bj)
; #pragma unroll
;                     for (int n = 0; n < 2; ++n) { f32x4 v = acc[ai][bj][m][n] * rs + *(const f32x4*)(bias + col0 + bj * 128 + n * 16);
;                         if (n == 0 && rope) { f32x4 pv;
; #pragma unroll
;                             for (int e = 0; e < 4; ++e) pv[e] = __shfl_xor(v[e], 32);
;                             const float sg = (fq < 2) ? -1.f : 1.f;
;                             v = v * cs + sg * (pv * sn); }
;                         *(u32x2*)(rowp + bj * 128 + n * 16) = pack4(v); } }
.LBB0_184:
	s_waitcnt vmcnt(0)
	v_mov_b32_e32 v82, v77
	v_mov_b32_e32 v83, v78
	v_mov_b32_e32 v77, v79
	v_pk_add_f32 v[76:77], v[82:83], v[76:77]
	v_mov_b32_e32 v78, v74
	v_mov_b32_e32 v79, v72
	v_mov_b32_e32 v72, v75
	v_pk_add_f32 v[72:73], v[78:79], v[72:73]
	v_add_f32_e32 v74, v76, v77
	v_add_f32_e32 v73, v74, v73
	v_mov_b32_e32 v74, v216
	v_mov_b32_e32 v75, v217
	v_mov_b32_e32 v76, v218
	v_mov_b32_e32 v77, v219
	v_add_f32_e32 v72, v72, v73
	v_fmamk_f32 v72, v72, 0x3a000000, v199
	v_cmp_gt_f32_e32 vcc, s9, v72
	v_mul_f32_e32 v73, 0x4b800000, v72
	s_nop 0
	v_cndmask_b32_e32 v72, v72, v73, vcc
	v_rsq_f32_e32 v72, v72
	s_nop 0
	v_mul_f32_e32 v73, 0x45800000, v72
	v_cndmask_b32_e32 v72, v72, v73, vcc
	s_and_b64 vcc, exec, s[4:5]
	v_pk_fma_f32 v[62:63], v[62:63], v[72:73], v[76:77] op_sel_hi:[1,0,1]
	v_pk_fma_f32 v[60:61], v[60:61], v[72:73], v[74:75] op_sel_hi:[1,0,1]
	s_cbranch_vccnz .LBB0_186
	v_cmp_lt_i32_e32 vcc, v207, v206
	s_nop 1
	v_cndmask_b32_e32 v73, v204, v207, vcc
	v_lshlrev_b32_e32 v73, 2, v73
	ds_bpermute_b32 v74, v73, v60
	ds_bpermute_b32 v76, v73, v62
	ds_bpermute_b32 v77, v73, v63
	ds_bpermute_b32 v75, v73, v61
	s_waitcnt lgkmcnt(0)
	v_pk_mul_f32 v[76:77], v[70:71], v[76:77]
	v_pk_mul_f32 v[74:75], v[68:69], v[74:75]
	v_pk_mul_f32 v[76:77], v[148:149], v[76:77]
	v_pk_mul_f32 v[74:75], v[146:147], v[74:75]
	v_pk_fma_f32 v[62:63], v[66:67], v[62:63], v[76:77]
	v_pk_fma_f32 v[60:61], v[64:65], v[60:61], v[74:75]
.LBB0_186:
	v_readlane_b32 s18, v250, 11
	v_readlane_b32 s19, v250, 12
	v_cvt_pk_bf16_f32 v60, v60, v61
	v_cvt_pk_bf16_f32 v61, v62, v63
	v_mov_b64_e32 v[74:75], s[18:19]
	v_mad_i64_i32 v[74:75], s[18:19], v80, s96, v[74:75]
	v_lshl_add_u64 v[74:75], v[158:159], 1, v[74:75]
	global_store_dwordx2 v[74:75], v[60:61], off
	v_mov_b32_e32 v76, v220
	v_mov_b32_e32 v77, v221
	v_mov_b32_e32 v78, v222
	v_mov_b32_e32 v79, v223
	v_mov_b32_e32 v73, v72
	v_mov_b32_e32 v60, v72
	v_mov_b32_e32 v61, v72
	s_and_b64 vcc, exec, s[4:5]
	v_pk_fma_f32 v[58:59], v[58:59], v[60:61], v[78:79]
	v_pk_fma_f32 v[56:57], v[56:57], v[72:73], v[76:77]
	s_nop 0
	v_cvt_pk_bf16_f32 v56, v56, v57
	v_cvt_pk_bf16_f32 v57, v58, v59
	global_store_dwordx2 v[74:75], v[56:57], off offset:32
	v_mov_b32_e32 v56, v224
	v_mov_b32_e32 v57, v225
	v_mov_b32_e32 v58, v226
	v_mov_b32_e32 v59, v227
	v_pk_fma_f32 v[54:55], v[54:55], v[60:61], v[58:59]
	v_pk_fma_f32 v[52:53], v[52:53], v[72:73], v[56:57]
	s_cbranch_vccnz .LBB0_188
	v_cmp_lt_i32_e32 vcc, v207, v206
	s_nop 1
	v_cndmask_b32_e32 v56, v204, v207, vcc
	v_lshlrev_b32_e32 v57, 2, v56
	ds_bpermute_b32 v56, v57, v52
	ds_bpermute_b32 v58, v57, v54
	ds_bpermute_b32 v59, v57, v55
	ds_bpermute_b32 v57, v57, v53
	s_waitcnt lgkmcnt(0)
	v_pk_mul_f32 v[58:59], v[70:71], v[58:59]
	v_pk_mul_f32 v[56:57], v[68:69], v[56:57]
	v_pk_mul_f32 v[58:59], v[148:149], v[58:59]
	v_pk_mul_f32 v[56:57], v[146:147], v[56:57]
	v_pk_fma_f32 v[54:55], v[66:67], v[54:55], v[58:59]
	v_pk_fma_f32 v[52:53], v[64:65], v[52:53], v[56:57]
.LBB0_188:
	s_nop 0
	v_cvt_pk_bf16_f32 v52, v52, v53
	v_cvt_pk_bf16_f32 v53, v54, v55
	global_store_dwordx2 v[74:75], v[52:53], off offset:256
	v_mov_b32_e32 v52, v228
	v_mov_b32_e32 v53, v229
	v_mov_b32_e32 v54, v230
	v_mov_b32_e32 v55, v231
	v_add_u32_e32 v64, 0x90, v174
	v_ashrrev_i32_e32 v65, 31, v64
	s_and_b64 vcc, exec, s[4:5]
	v_pk_fma_f32 v[50:51], v[50:51], v[60:61], v[54:55]
	v_pk_fma_f32 v[48:49], v[48:49], v[72:73], v[52:53]
	s_nop 0
	v_cvt_pk_bf16_f32 v48, v48, v49
	v_cvt_pk_bf16_f32 v49, v50, v51
	global_store_dwordx2 v[74:75], v[48:49], off offset:288
	v_lshlrev_b64 v[48:49], 5, v[64:65]
	v_lshl_add_u64 v[48:49], s[20:21], 0, v[48:49]
	global_load_dwordx4 v[56:59], v[48:49], off offset:16
	global_load_dwordx4 v[60:63], v[48:49], off
	s_cbranch_vccnz .LBB0_190
	v_lshlrev_b32_e32 v48, 3, v64
	v_ashrrev_i32_e32 v49, 31, v48
	v_lshlrev_b64 v[48:49], 2, v[48:49]
	v_lshl_add_u64 v[50:51], v[152:153], 0, v[48:49]
	v_lshl_add_u64 v[52:53], v[150:151], 0, v[48:49]
	global_load_dwordx4 v[48:51], v[50:51], off
	s_nop 0
	global_load_dwordx4 v[52:55], v[52:53], off
	s_branch .LBB0_191

; DEV u32x2 pack4(f32x4 a) { u32x2 w; w.x = cvt_pk_bf16(a[0], a[1]); w.y = cvt_pk_bf16(a[2], a[3]); return w; }
;     DEV void operator()(AccRef acc, const pg8::Unit& u, int wr, int wc, int fr, int fq) const {
;     ...
;             for (int m = 0; m < 4; ++m) { const int row = row0 + ai * 128 + m * 16; u16* rowp = O + (size_t)row * 2560 + col0; const float rs = rowscale(ss, row);
;                 f32x4 cs = (f32x4){1.f, 1.f, 1.f, 1.f}, sn = (f32x4){0.f, 0.f, 0.f, 0.f};
;                 if (rope) { cs = *(const f32x4*)(cosT + row * 8 + 4 * (fq & 1)); sn = *(const f32x4*)(sinT + row * 8 + 4 * (fq & 1)); }
; #pragma unroll
;                 for (int bj = 0; bj < 2; ++bj)
; #pragma unroll
;                     for (int n = 0; n < 2; ++n) { f32x4 v = acc[ai][bj][m][n] * rs + *(const f32x4*)(bias + col0 + bj * 128 + n * 16);
;                         if (n == 0 && rope) { f32x4 pv;
; #pragma unroll
;                             for (int e = 0; e < 4; ++e) pv[e] = __shfl_xor(v[e], 32);
;                             const float sg = (fq < 2) ? -1.f : 1.f;
;                             v = v * cs + sg * (pv * sn); }
;                         *(u32x2*)(rowp + bj * 128 + n * 16) = pack4(v); } }
.LBB0_191:
	s_waitcnt vmcnt(0)
	v_mov_b32_e32 v66, v61
	v_mov_b32_e32 v67, v62
	v_mov_b32_e32 v61, v63
	v_pk_add_f32 v[60:61], v[66:67], v[60:61]
	v_mov_b32_e32 v62, v58
	v_mov_b32_e32 v63, v56
	v_mov_b32_e32 v56, v59
	v_pk_add_f32 v[56:57], v[62:63], v[56:57]
	v_add_f32_e32 v58, v60, v61
	v_add_f32_e32 v57, v58, v57
	v_mov_b32_e32 v58, v216
	v_mov_b32_e32 v59, v217
	v_mov_b32_e32 v60, v218
	v_mov_b32_e32 v61, v219
	v_add_f32_e32 v56, v56, v57
	v_fmamk_f32 v56, v56, 0x3a000000, v199
	v_cmp_gt_f32_e32 vcc, s9, v56
	v_mul_f32_e32 v57, 0x4b800000, v56
	s_nop 0
	v_cndmask_b32_e32 v56, v56, v57, vcc
	v_rsq_f32_e32 v56, v56
	s_nop 0
	v_mul_f32_e32 v57, 0x45800000, v56
	v_cndmask_b32_e32 v56, v56, v57, vcc
	s_and_b64 vcc, exec, s[4:5]
	v_pk_fma_f32 v[46:47], v[46:47], v[56:57], v[60:61] op_sel_hi:[1,0,1]
	v_pk_fma_f32 v[44:45], v[44:45], v[56:57], v[58:59] op_sel_hi:[1,0,1]
	s_cbranch_vccnz .LBB0_193
	v_cmp_lt_i32_e32 vcc, v207, v206
	s_nop 1
	v_cndmask_b32_e32 v57, v204, v207, vcc
	v_lshlrev_b32_e32 v57, 2, v57
	ds_bpermute_b32 v58, v57, v44
	ds_bpermute_b32 v60, v57, v46
	ds_bpermute_b32 v61, v57, v47
	ds_bpermute_b32 v59, v57, v45
	s_waitcnt lgkmcnt(0)
	v_pk_mul_f32 v[60:61], v[54:55], v[60:61]
	v_pk_mul_f32 v[58:59], v[52:53], v[58:59]
	v_pk_mul_f32 v[60:61], v[148:149], v[60:61]
	v_pk_mul_f32 v[58:59], v[146:147], v[58:59]
	v_pk_fma_f32 v[46:47], v[50:51], v[46:47], v[60:61]
	v_pk_fma_f32 v[44:45], v[48:49], v[44:45], v[58:59]
.LBB0_193:
	v_readlane_b32 s18, v250, 11
	v_readlane_b32 s19, v250, 12
	v_cvt_pk_bf16_f32 v44, v44, v45
	v_cvt_pk_bf16_f32 v45, v46, v47
	v_mov_b64_e32 v[58:59], s[18:19]
	v_mad_i64_i32 v[58:59], s[18:19], v64, s96, v[58:59]
	v_lshl_add_u64 v[58:59], v[158:159], 1, v[58:59]
	global_store_dwordx2 v[58:59], v[44:45], off
	v_mov_b32_e32 v60, v220
	v_mov_b32_e32 v61, v221
	v_mov_b32_e32 v62, v222
	v_mov_b32_e32 v63, v223
	v_mov_b32_e32 v57, v56
	v_mov_b32_e32 v44, v56
	v_mov_b32_e32 v45, v56
	s_and_b64 vcc, exec, s[4:5]
	v_pk_fma_f32 v[42:43], v[42:43], v[44:45], v[62:63]
	v_pk_fma_f32 v[40:41], v[40:41], v[56:57], v[60:61]
	s_nop 0
	v_cvt_pk_bf16_f32 v40, v40, v41
	v_cvt_pk_bf16_f32 v41, v42, v43
	global_store_dwordx2 v[58:59], v[40:41], off offset:32
	v_mov_b32_e32 v40, v224
	v_mov_b32_e32 v41, v225
	v_mov_b32_e32 v42, v226
	v_mov_b32_e32 v43, v227
	v_pk_fma_f32 v[38:39], v[38:39], v[44:45], v[42:43]
	v_pk_fma_f32 v[36:37], v[36:37], v[56:57], v[40:41]
	s_cbranch_vccnz .LBB0_195
	v_cmp_lt_i32_e32 vcc, v207, v206
	s_nop 1
	v_cndmask_b32_e32 v40, v204, v207, vcc
	v_lshlrev_b32_e32 v41, 2, v40
	ds_bpermute_b32 v40, v41, v36
	ds_bpermute_b32 v42, v41, v38
	ds_bpermute_b32 v43, v41, v39
	ds_bpermute_b32 v41, v41, v37
	s_waitcnt lgkmcnt(0)
	v_pk_mul_f32 v[42:43], v[54:55], v[42:43]
	v_pk_mul_f32 v[40:41], v[52:53], v[40:41]
	v_pk_mul_f32 v[42:43], v[148:149], v[42:43]
	v_pk_mul_f32 v[40:41], v[146:147], v[40:41]
	v_pk_fma_f32 v[38:39], v[50:51], v[38:39], v[42:43]
	v_pk_fma_f32 v[36:37], v[48:49], v[36:37], v[40:41]
.LBB0_195:
	s_nop 0
	v_cvt_pk_bf16_f32 v36, v36, v37
	v_cvt_pk_bf16_f32 v37, v38, v39
	global_store_dwordx2 v[58:59], v[36:37], off offset:256
	v_mov_b32_e32 v36, v228
	v_mov_b32_e32 v37, v229
	v_mov_b32_e32 v38, v230
	v_mov_b32_e32 v39, v231
	v_add_u32_e32 v48, 0xa0, v174
	v_ashrrev_i32_e32 v49, 31, v48
	s_and_b64 vcc, exec, s[4:5]
	v_pk_fma_f32 v[34:35], v[34:35], v[44:45], v[38:39]
	v_pk_fma_f32 v[32:33], v[32:33], v[56:57], v[36:37]
	s_nop 0
	v_cvt_pk_bf16_f32 v32, v32, v33
	v_cvt_pk_bf16_f32 v33, v34, v35
	global_store_dwordx2 v[58:59], v[32:33], off offset:288
	v_lshlrev_b64 v[32:33], 5, v[48:49]
	v_lshl_add_u64 v[32:33], s[20:21], 0, v[32:33]
	global_load_dwordx4 v[40:43], v[32:33], off offset:16
	global_load_dwordx4 v[44:47], v[32:33], off
	s_cbranch_vccnz .LBB0_197
	v_lshlrev_b32_e32 v32, 3, v48
	v_ashrrev_i32_e32 v33, 31, v32
	v_lshlrev_b64 v[32:33], 2, v[32:33]
	v_lshl_add_u64 v[34:35], v[152:153], 0, v[32:33]
	v_lshl_add_u64 v[36:37], v[150:151], 0, v[32:33]
	global_load_dwordx4 v[32:35], v[34:35], off
	s_nop 0
	global_load_dwordx4 v[36:39], v[36:37], off
	s_branch .LBB0_198

; DEV u32x2 pack4(f32x4 a) { u32x2 w; w.x = cvt_pk_bf16(a[0], a[1]); w.y = cvt_pk_bf16(a[2], a[3]); return w; }
;     DEV void operator()(AccRef acc, const pg8::Unit& u, int wr, int wc, int fr, int fq) const {
;     ...
;             for (int m = 0; m < 4; ++m) { const int row = row0 + ai * 128 + m * 16; u16* rowp = O + (size_t)row * 2560 + col0; const float rs = rowscale(ss, row);
;                 f32x4 cs = (f32x4){1.f, 1.f, 1.f, 1.f}, sn = (f32x4){0.f, 0.f, 0.f, 0.f};
;                 if (rope) { cs = *(const f32x4*)(cosT + row * 8 + 4 * (fq & 1)); sn = *(const f32x4*)(sinT + row * 8 + 4 * (fq & 1)); }
; #pragma unroll
;                 for (int bj = 0; bj < 2; ++bj)
; #pragma unroll
;                     for (int n = 0; n < 2; ++n) { f32x4 v = acc[ai][bj][m][n] * rs + *(const f32x4*)(bias + col0 + bj * 128 + n * 16);
;                         if (n == 0 && rope) { f32x4 pv;
; #pragma unroll
;                             for (int e = 0; e < 4; ++e) pv[e] = __shfl_xor(v[e], 32);
;                             const float sg = (fq < 2) ? -1.f : 1.f;
;                             v = v * cs + sg * (pv * sn); }
;                         *(u32x2*)(rowp + bj * 128 + n * 16) = pack4(v); } }
.LBB0_198:
	s_waitcnt vmcnt(0)
	v_mov_b32_e32 v50, v45
	v_mov_b32_e32 v51, v46
	v_mov_b32_e32 v45, v47
	v_pk_add_f32 v[44:45], v[50:51], v[44:45]
	v_mov_b32_e32 v46, v42
	v_mov_b32_e32 v47, v40
	v_mov_b32_e32 v40, v43
	v_pk_add_f32 v[40:41], v[46:47], v[40:41]
	v_add_f32_e32 v42, v44, v45
	v_add_f32_e32 v41, v42, v41
	v_mov_b32_e32 v42, v216
	v_mov_b32_e32 v43, v217
	v_mov_b32_e32 v44, v218
	v_mov_b32_e32 v45, v219
	v_add_f32_e32 v40, v40, v41
	v_fmamk_f32 v40, v40, 0x3a000000, v199
	v_cmp_gt_f32_e32 vcc, s9, v40
	v_mul_f32_e32 v41, 0x4b800000, v40
	s_nop 0
	v_cndmask_b32_e32 v40, v40, v41, vcc
	v_rsq_f32_e32 v40, v40
	s_nop 0
	v_mul_f32_e32 v41, 0x45800000, v40
	v_cndmask_b32_e32 v40, v40, v41, vcc
	s_and_b64 vcc, exec, s[4:5]
	v_pk_fma_f32 v[30:31], v[30:31], v[40:41], v[44:45] op_sel_hi:[1,0,1]
	v_pk_fma_f32 v[28:29], v[28:29], v[40:41], v[42:43] op_sel_hi:[1,0,1]
	s_cbranch_vccnz .LBB0_200
	v_cmp_lt_i32_e32 vcc, v207, v206
	s_nop 1
	v_cndmask_b32_e32 v41, v204, v207, vcc
	v_lshlrev_b32_e32 v41, 2, v41
	ds_bpermute_b32 v42, v41, v28
	ds_bpermute_b32 v44, v41, v30
	ds_bpermute_b32 v45, v41, v31
	ds_bpermute_b32 v43, v41, v29
	s_waitcnt lgkmcnt(0)
	v_pk_mul_f32 v[44:45], v[38:39], v[44:45]
	v_pk_mul_f32 v[42:43], v[36:37], v[42:43]
	v_pk_mul_f32 v[44:45], v[148:149], v[44:45]
	v_pk_mul_f32 v[42:43], v[146:147], v[42:43]
	v_pk_fma_f32 v[30:31], v[34:35], v[30:31], v[44:45]
	v_pk_fma_f32 v[28:29], v[32:33], v[28:29], v[42:43]
.LBB0_200:
	v_readlane_b32 s18, v250, 11
	v_readlane_b32 s19, v250, 12
	v_cvt_pk_bf16_f32 v28, v28, v29
	v_cvt_pk_bf16_f32 v29, v30, v31
	v_mov_b64_e32 v[42:43], s[18:19]
	v_mad_i64_i32 v[42:43], s[18:19], v48, s96, v[42:43]
	v_lshl_add_u64 v[42:43], v[158:159], 1, v[42:43]
	global_store_dwordx2 v[42:43], v[28:29], off
	v_mov_b32_e32 v44, v220
	v_mov_b32_e32 v45, v221
	v_mov_b32_e32 v46, v222
	v_mov_b32_e32 v47, v223
	v_mov_b32_e32 v41, v40
	v_mov_b32_e32 v28, v40
	v_mov_b32_e32 v29, v40
	s_and_b64 vcc, exec, s[4:5]
	v_pk_fma_f32 v[26:27], v[26:27], v[28:29], v[46:47]
	v_pk_fma_f32 v[24:25], v[24:25], v[40:41], v[44:45]
	s_nop 0
	v_cvt_pk_bf16_f32 v24, v24, v25
	v_cvt_pk_bf16_f32 v25, v26, v27
	global_store_dwordx2 v[42:43], v[24:25], off offset:32
	v_mov_b32_e32 v24, v224
	v_mov_b32_e32 v25, v225
	v_mov_b32_e32 v26, v226
	v_mov_b32_e32 v27, v227
	v_pk_fma_f32 v[22:23], v[22:23], v[28:29], v[26:27]
	v_pk_fma_f32 v[20:21], v[20:21], v[40:41], v[24:25]
	s_cbranch_vccnz .LBB0_202
	v_cmp_lt_i32_e32 vcc, v207, v206
	s_nop 1
	v_cndmask_b32_e32 v24, v204, v207, vcc
	v_lshlrev_b32_e32 v25, 2, v24
	ds_bpermute_b32 v24, v25, v20
	ds_bpermute_b32 v26, v25, v22
	ds_bpermute_b32 v27, v25, v23
	ds_bpermute_b32 v25, v25, v21
	s_waitcnt lgkmcnt(0)
	v_pk_mul_f32 v[26:27], v[38:39], v[26:27]
	v_pk_mul_f32 v[24:25], v[36:37], v[24:25]
	v_pk_mul_f32 v[26:27], v[148:149], v[26:27]
	v_pk_mul_f32 v[24:25], v[146:147], v[24:25]
	v_pk_fma_f32 v[22:23], v[34:35], v[22:23], v[26:27]
	v_pk_fma_f32 v[20:21], v[32:33], v[20:21], v[24:25]
.LBB0_202:
	s_nop 0
	v_cvt_pk_bf16_f32 v20, v20, v21
	v_cvt_pk_bf16_f32 v21, v22, v23
	global_store_dwordx2 v[42:43], v[20:21], off offset:256
	v_mov_b32_e32 v20, v228
	v_mov_b32_e32 v21, v229
	v_mov_b32_e32 v22, v230
	v_mov_b32_e32 v23, v231
	v_add_u32_e32 v32, 0xb0, v174
	v_ashrrev_i32_e32 v33, 31, v32
	s_and_b64 vcc, exec, s[4:5]
	v_pk_fma_f32 v[18:19], v[18:19], v[28:29], v[22:23]
	v_pk_fma_f32 v[16:17], v[16:17], v[40:41], v[20:21]
	s_nop 0
	v_cvt_pk_bf16_f32 v16, v16, v17
	v_cvt_pk_bf16_f32 v17, v18, v19
	global_store_dwordx2 v[42:43], v[16:17], off offset:288
	v_lshlrev_b64 v[16:17], 5, v[32:33]
	v_lshl_add_u64 v[16:17], s[20:21], 0, v[16:17]
	global_load_dwordx4 v[24:27], v[16:17], off offset:16
	global_load_dwordx4 v[28:31], v[16:17], off
	s_cbranch_vccnz .LBB0_204
	v_lshlrev_b32_e32 v16, 3, v32
	v_ashrrev_i32_e32 v17, 31, v16
	v_lshlrev_b64 v[16:17], 2, v[16:17]
	v_lshl_add_u64 v[18:19], v[152:153], 0, v[16:17]
	v_lshl_add_u64 v[20:21], v[150:151], 0, v[16:17]
	global_load_dwordx4 v[16:19], v[18:19], off
	s_nop 0
	global_load_dwordx4 v[20:23], v[20:21], off
	s_branch .LBB0_205

; DEV u32x2 pack4(f32x4 a) { u32x2 w; w.x = cvt_pk_bf16(a[0], a[1]); w.y = cvt_pk_bf16(a[2], a[3]); return w; }
;     DEV void operator()(AccRef acc, const pg8::Unit& u, int wr, int wc, int fr, int fq) const {
;     ...
;             for (int m = 0; m < 4; ++m) { const int row = row0 + ai * 128 + m * 16; u16* rowp = O + (size_t)row * 2560 + col0; const float rs = rowscale(ss, row);
;                 f32x4 cs = (f32x4){1.f, 1.f, 1.f, 1.f}, sn = (f32x4){0.f, 0.f, 0.f, 0.f};
;                 if (rope) { cs = *(const f32x4*)(cosT + row * 8 + 4 * (fq & 1)); sn = *(const f32x4*)(sinT + row * 8 + 4 * (fq & 1)); }
; #pragma unroll
;                 for (int bj = 0; bj < 2; ++bj)
; #pragma unroll
;                     for (int n = 0; n < 2; ++n) { f32x4 v = acc[ai][bj][m][n] * rs + *(const f32x4*)(bias + col0 + bj * 128 + n * 16);
;                         if (n == 0 && rope) { f32x4 pv;
; #pragma unroll
;                             for (int e = 0; e < 4; ++e) pv[e] = __shfl_xor(v[e], 32);
;                             const float sg = (fq < 2) ? -1.f : 1.f;
;                             v = v * cs + sg * (pv * sn); }
;                         *(u32x2*)(rowp + bj * 128 + n * 16) = pack4(v); } }
.LBB0_205:
	s_waitcnt vmcnt(0)
	v_mov_b32_e32 v34, v29
	v_mov_b32_e32 v35, v30
	v_mov_b32_e32 v29, v31
	v_pk_add_f32 v[28:29], v[34:35], v[28:29]
	v_mov_b32_e32 v30, v26
	v_mov_b32_e32 v31, v24
	v_mov_b32_e32 v24, v27
	v_pk_add_f32 v[24:25], v[30:31], v[24:25]
	v_add_f32_e32 v26, v28, v29
	v_add_f32_e32 v25, v26, v25
	v_mov_b32_e32 v26, v216
	v_mov_b32_e32 v27, v217
	v_mov_b32_e32 v28, v218
	v_mov_b32_e32 v29, v219
	v_add_f32_e32 v24, v24, v25
	v_fmamk_f32 v24, v24, 0x3a000000, v199
	v_cmp_gt_f32_e32 vcc, s9, v24
	v_mul_f32_e32 v25, 0x4b800000, v24
	s_nop 0
	v_cndmask_b32_e32 v24, v24, v25, vcc
	v_rsq_f32_e32 v24, v24
	s_nop 0
	v_mul_f32_e32 v25, 0x45800000, v24
	v_cndmask_b32_e32 v24, v24, v25, vcc
	s_and_b64 vcc, exec, s[4:5]
	v_pk_fma_f32 v[14:15], v[14:15], v[24:25], v[28:29] op_sel_hi:[1,0,1]
	v_pk_fma_f32 v[12:13], v[12:13], v[24:25], v[26:27] op_sel_hi:[1,0,1]
	s_cbranch_vccnz .LBB0_207
	v_cmp_lt_i32_e32 vcc, v207, v206
	s_nop 1
	v_cndmask_b32_e32 v25, v204, v207, vcc
	v_lshlrev_b32_e32 v25, 2, v25
	ds_bpermute_b32 v26, v25, v12
	ds_bpermute_b32 v28, v25, v14
	ds_bpermute_b32 v29, v25, v15
	ds_bpermute_b32 v27, v25, v13
	s_waitcnt lgkmcnt(0)
	v_pk_mul_f32 v[28:29], v[22:23], v[28:29]
	v_pk_mul_f32 v[26:27], v[20:21], v[26:27]
	v_pk_mul_f32 v[28:29], v[148:149], v[28:29]
	v_pk_mul_f32 v[26:27], v[146:147], v[26:27]
	v_pk_fma_f32 v[14:15], v[18:19], v[14:15], v[28:29]
	v_pk_fma_f32 v[12:13], v[16:17], v[12:13], v[26:27]
.LBB0_207:
	v_readlane_b32 s18, v250, 11
	v_readlane_b32 s19, v250, 12
	v_cvt_pk_bf16_f32 v12, v12, v13
	v_cvt_pk_bf16_f32 v13, v14, v15
	v_mov_b64_e32 v[26:27], s[18:19]
	v_mad_i64_i32 v[26:27], s[18:19], v32, s96, v[26:27]
	v_lshl_add_u64 v[26:27], v[158:159], 1, v[26:27]
	global_store_dwordx2 v[26:27], v[12:13], off
	v_mov_b32_e32 v28, v220
	v_mov_b32_e32 v29, v221
	v_mov_b32_e32 v30, v222
	v_mov_b32_e32 v31, v223
	v_mov_b32_e32 v25, v24
	v_mov_b32_e32 v12, v24
	v_mov_b32_e32 v13, v24
	s_and_b64 vcc, exec, s[4:5]
	v_pk_fma_f32 v[10:11], v[10:11], v[12:13], v[30:31]
	v_pk_fma_f32 v[8:9], v[8:9], v[24:25], v[28:29]
	s_nop 0
	v_cvt_pk_bf16_f32 v8, v8, v9
	v_cvt_pk_bf16_f32 v9, v10, v11
	global_store_dwordx2 v[26:27], v[8:9], off offset:32
	v_mov_b32_e32 v8, v224
	v_mov_b32_e32 v9, v225
	v_mov_b32_e32 v10, v226
	v_mov_b32_e32 v11, v227
	v_pk_fma_f32 v[6:7], v[6:7], v[12:13], v[10:11]
	v_pk_fma_f32 v[4:5], v[4:5], v[24:25], v[8:9]
	s_cbranch_vccnz .LBB0_148
	v_cmp_lt_i32_e32 vcc, v207, v206
	s_nop 1
	v_cndmask_b32_e32 v8, v204, v207, vcc
	v_lshlrev_b32_e32 v9, 2, v8
	ds_bpermute_b32 v8, v9, v4
	ds_bpermute_b32 v10, v9, v6
	ds_bpermute_b32 v11, v9, v7
	ds_bpermute_b32 v9, v9, v5
	s_waitcnt lgkmcnt(0)
	v_pk_mul_f32 v[10:11], v[22:23], v[10:11]
	v_pk_mul_f32 v[8:9], v[20:21], v[8:9]
	v_pk_mul_f32 v[10:11], v[148:149], v[10:11]
	v_pk_mul_f32 v[8:9], v[146:147], v[8:9]
	v_pk_fma_f32 v[6:7], v[18:19], v[6:7], v[10:11]
	v_pk_fma_f32 v[4:5], v[16:17], v[4:5], v[8:9]
	s_branch .LBB0_148

; DEV int otid() { int t = (int)threadIdx.x; asm volatile("" : "+v"(t)); return t; }
; template <bool GAIN>
; DEV void conv_weight_t(const float* __restrict__ W, u16* __restrict__ Wt, int K, int Nsrc, int Ndst, int mode, int gtid, int gthreads, const float* __restrict__ gain) {
;     const int kblocks = K >> 6; const int nitems = Ndst * kblocks;
;     for (int it = gtid; it < nitems; it += gthreads) {
;         const int kb = __builtin_amdgcn_readfirstlane(it / Ndst), n = it - kb * Ndst;
;         int src = n; if (mode == 1) { const int pn = n >> 8, bj = (n >> 7) & 1, w = n & 127; src = bj * 5632 + pn * 128 + w; }
;         const bool valid = src < Nsrc; const float zs = valid ? 1.f : 0.f;
;         const float* s = W + (size_t)(kb * 64) * Nsrc + (valid ? src : 0);
;         float v[64];
; #pragma unroll
;         for (int i = 0; i < 64; ++i) v[i] = s[(size_t)i * Nsrc];
; DEV void idle_conv(const P& p, int job, int nwg, int bx, int G) {
;     const int first_idle = nwg % G;
;     if (first_idle == 0 || bx < first_idle) return;
;     conv_job(p, job, (bx - first_idle) * 512 + otid(), (G - first_idle) * 512);
; }
.LBB0_366:
	s_lshr_b64 s[4:5], s[4:5], 26
	s_mul_i32 s4, s4, s30
	s_sub_i32 s4, 64, s4
	s_sub_i32 s5, s4, s30
	s_cmp_ge_u32 s4, s30
	s_cselect_b32 s4, s5, s4
	s_sub_i32 s5, s4, s30
	s_cmp_ge_u32 s4, s30
	s_cselect_b32 s4, s5, s4
	v_readlane_b32 s5, v250, 7
	s_nop 0
	s_cmp_eq_u32 s5, 9
	s_cselect_b32 s5, 8, 0
	s_cmp_eq_u32 s30, 0x100
	s_cselect_b32 s5, s5, 0
	s_add_i32 s4, s4, s5
	s_cmp_eq_u32 s4, 0
	v_readlane_b32 s5, v254, 20
	s_cselect_b64 s[6:7], -1, 0
	s_cmp_lt_i32 s5, s4
	s_cselect_b64 s[10:11], -1, 0
	s_or_b64 s[6:7], s[6:7], s[10:11]
	s_and_b64 vcc, exec, s[6:7]
	s_cbranch_vccnz .LBB0_383
	v_readlane_b32 s5, v254, 20
	s_sub_i32 s5, s5, s4
	v_mov_b32_e32 v33, v198
	s_and_b64 vcc, exec, s[0:1]
	v_lshl_add_u32 v84, s5, 9, v33
	v_readlane_b32 s5, v254, 23
	s_sub_i32 s4, s5, s4
	s_lshl_b32 s12, s4, 9
	s_mov_b64 s[4:5], -1
	v_cmp_gt_i32_e64 s[0:1], s59, v84
	s_cbranch_vccz .LBB0_372
	s_mov_b64 s[4:5], exec
	v_readlane_b32 s16, v250, 27
	s_and_b64 s[0:1], s[4:5], s[0:1]
	v_readlane_b32 s13, v250, 25
	v_readlane_b32 s14, v250, 26
	v_readlane_b32 s17, v250, 28
	v_readlane_b32 s15, v250, 29
	v_readlane_b32 s18, v250, 30
	s_mov_b32 s19, 0x16000
	s_mov_b32 s20, 0x2c000
	s_mov_b32 s21, 0x42000
	s_mov_b32 s22, 0x58000
	s_mov_b32 s23, 0x6e000
	s_mov_b32 s24, 0xb000
	s_movk_i32 s25, 0x2c00
	s_mov_b32 s26, 0x21000
	s_mov_b32 s27, 0x37000
	s_mov_b32 s28, 0x4d000
	s_mov_b32 s29, 0x63000
	s_mov_b32 s30, 0x79000
	s_mov_b32 s31, 0x84000
	s_mov_b32 s34, 0x8f000
	s_mov_b32 s35, 0x9a000
	s_mov_b32 s36, 0xa5000
	s_mov_b32 s37, 0xb0000
	s_mov_b32 s38, 0xbb000
	s_mov_b32 s39, 0xc6000
	s_mov_b32 s40, 0xd1000
	s_mov_b32 s41, 0xdc000
	s_mov_b32 s42, 0xe7000
	s_mov_b32 s43, 0xf2000
	s_mov_b32 s44, 0xfd000
	s_mov_b32 s45, 0x108000
	s_mov_b32 s46, 0x113000
	s_mov_b32 s47, 0x11e000
	s_mov_b32 s48, 0x129000
	s_mov_b32 s49, 0x134000
	s_mov_b32 s50, 0x13f000
	s_mov_b32 s51, 0x14a000
	s_mov_b32 s52, 0x155000
	s_mov_b32 s53, 0x160000
	s_mov_b32 s54, 0x16b000
	s_mov_b32 s55, 0x176000
	s_mov_b32 s56, 0x181000
	s_mov_b32 s57, 0x18c000
	s_mov_b32 s58, 0x197000
	s_mov_b32 s59, 0x1a2000
	s_mov_b32 s60, 0x1ad000
	s_mov_b32 s61, 0x1b8000
	s_mov_b32 s62, 0x1c3000
	s_mov_b32 s63, 0x1ce000
	s_mov_b32 s64, 0x1d9000
	s_mov_b32 s65, 0x1e4000
	s_mov_b32 s66, 0x1ef000
	s_mov_b32 s67, 0x1fa000
	s_mov_b32 s68, 0x205000
	s_mov_b32 s69, 0x210000
	s_mov_b32 s72, 0x21b000
	s_mov_b32 s74, 0x226000
	s_mov_b32 s75, 0x231000
	s_mov_b32 s76, 0x23c000
	s_mov_b32 s77, 0x247000
	s_mov_b32 s78, 0x252000
	s_mov_b32 s79, 0x25d000
	s_mov_b32 s82, 0x268000
	s_mov_b32 s83, 0x273000
	s_mov_b32 s84, 0x27e000
	s_mov_b32 s85, 0x289000
	s_mov_b32 s86, 0x294000
	s_mov_b32 s87, 0x29f000
	s_mov_b32 s92, 0x2aa000
	s_mov_b32 s94, 0x2b5000
	s_mov_b32 s95, 0x57fff
	s_mov_b64 exec, s[0:1]
	s_cbranch_execz .LBB0_371
	v_and_b32_e32 v85, 0x7f, v33
	s_mov_b64 s[6:7], 0
	v_mov_b32_e32 v86, v84
